# grid barriers 1-7 hand-written (L1 invalidate at arrival, all workgroups poll the top generation, no per-XCC generation hop); seam 7 keeps the guarded write-back skip
# speedup vs baseline: 1.0043x; 1.0043x over previous
; __device__ __forceinline__ unsigned xb_ld(unsigned* p)              { return __hip_atomic_load(p, __ATOMIC_RELAXED, __HIP_MEMORY_SCOPE_AGENT); }
; __device__ __forceinline__ unsigned xb_add(unsigned* p, unsigned v) { return __hip_atomic_fetch_add(p, v, __ATOMIC_RELAXED, __HIP_MEMORY_SCOPE_AGENT); }
; #define XB_SPIN(cond, bar) do { unsigned _sp = 0; while (cond) { __builtin_amdgcn_s_sleep(1); \
;     if ((++_sp & 255u) == 0u) { if (xb_ld(&(bar)[XB_TMO])) break; if (_sp > XB_SPIN_CAP) { atomicAdd(&(bar)[XB_TMO], 1u); break; } } } } while (0)
; __device__ __forceinline__ void xcd_barrier(const XcdBarrier& b) {
;     asm volatile("s_waitcnt vmcnt(0)" ::: "memory");
;     __syncthreads();
;     if (threadIdx.x == 0) {
;         unsigned* bar = b.bar;
;         __builtin_amdgcn_s_waitcnt(0);
;         unsigned nloc = b.st[0], nx = b.st[1];
;         if (nloc == 0u) { xcd_barrier_complete(bar, b.x, nloc, nx); b.st[0] = nloc; b.st[1] = nx; }
;         const unsigned old = xb_add(&bar[XB_XSUB(b.x)], 1u);
;         const unsigned gen = old / nloc;
;         if (old + 1u == (gen + 1u) * nloc) {
;             __builtin_amdgcn_fence(__ATOMIC_RELEASE, "agent");
;             asm volatile("s_waitcnt vmcnt(0)" ::: "memory");
;             const unsigned og = xb_add(&bar[XB_TOP], 1u);
;             const unsigned tg = og / nx;
;             if (og + 1u == (tg + 1u) * nx) xb_add(&bar[XB_TOPGEN], 1u);
;             else XB_SPIN(xb_ld(&bar[XB_TOPGEN]) == tg, bar);
;             __builtin_amdgcn_fence(__ATOMIC_ACQUIRE, "agent");
;             xb_add(&bar[XB_XGEN(b.x)], 1u);
;             asm volatile("s_waitcnt vmcnt(0)" ::: "memory");
;         } else {
;             XB_SPIN(xb_ld(&bar[XB_XGEN(b.x)]) == gen, bar);
;             __builtin_amdgcn_fence(__ATOMIC_ACQUIRE, "agent");
;             asm volatile("s_waitcnt vmcnt(0)" ::: "memory");
;         }
;     }
;     __syncthreads();
; }
.LBB0_441:
	s_cmp_gt_i32 s77, 2
	s_cselect_b64 s[6:7], -1, 0
	s_and_b64 s[4:5], s[8:9], s[6:7]
	s_andn2_b64 vcc, exec, s[4:5]
	s_cbranch_vccnz .LBB0_495
	s_waitcnt vmcnt(0) lgkmcnt(0)
	s_barrier
	s_and_saveexec_b64 s[8:9], s[96:97]
	s_cbranch_execz .Lfb1_end
	buffer_inv sc1
	v_mov_b32_e32 v1, 0x20160
	ds_read2_b32 v[2:3], v1 offset1:1
	s_lshl_b32 s1, s0, 8
	s_add_u32 s10, s78, s1
	s_addc_u32 s11, s79, 0
	v_mov_b32_e32 v4, 0x1000
	v_mov_b32_e32 v5, 1
	global_atomic_add v6, v4, v5, s[10:11] offset:1024 sc0
	s_waitcnt vmcnt(0) lgkmcnt(0)
	v_readfirstlane_b32 s3, v6
	v_readfirstlane_b32 s12, v2
	v_readfirstlane_b32 s13, v3
	s_add_i32 s3, s3, 1
	s_mul_i32 s1, s12, 2
	s_cmp_lg_u32 s3, s1
	s_cbranch_scc1 .Lfb1_spin
	buffer_wbl2 sc1
	s_waitcnt vmcnt(0)
.Lfb1_nowb:
	v_mov_b32_e32 v4, 0x3000
	global_atomic_add v6, v4, v5, s[78:79] offset:1024 sc0
	s_waitcnt vmcnt(0)
	v_readfirstlane_b32 s3, v6
	s_add_i32 s3, s3, 1
	s_mul_i32 s13, s13, 2
	s_cmp_lg_u32 s3, s13
	s_cbranch_scc1 .Lfb1_spin
	v_mov_b32_e32 v4, 0x3400
	global_atomic_add v4, v5, s[78:79] offset:256

; __device__ __forceinline__ unsigned xb_ld(unsigned* p)              { return __hip_atomic_load(p, __ATOMIC_RELAXED, __HIP_MEMORY_SCOPE_AGENT); }
; __device__ __forceinline__ unsigned xb_add(unsigned* p, unsigned v) { return __hip_atomic_fetch_add(p, v, __ATOMIC_RELAXED, __HIP_MEMORY_SCOPE_AGENT); }
; #define XB_SPIN(cond, bar) do { unsigned _sp = 0; while (cond) { __builtin_amdgcn_s_sleep(1); \
;     if ((++_sp & 255u) == 0u) { if (xb_ld(&(bar)[XB_TMO])) break; if (_sp > XB_SPIN_CAP) { atomicAdd(&(bar)[XB_TMO], 1u); break; } } } } while (0)
; __device__ __forceinline__ void xcd_barrier(const XcdBarrier& b) {
;     ...
;             const unsigned og = xb_add(&bar[XB_TOP], 1u);
;             const unsigned tg = og / nx;
;             if (og + 1u == (tg + 1u) * nx) xb_add(&bar[XB_TOPGEN], 1u);
;             else XB_SPIN(xb_ld(&bar[XB_TOPGEN]) == tg, bar);
;             __builtin_amdgcn_fence(__ATOMIC_ACQUIRE, "agent");
;             xb_add(&bar[XB_XGEN(b.x)], 1u);
.Lfb1_poll:
	global_load_dword v6, v4, s[78:79] offset:256 sc1
	s_waitcnt vmcnt(0)
	v_readfirstlane_b32 s3, v6
	s_cmp_lg_u32 s3, 1
	s_cbranch_scc1 .Lfb1_end
	s_sleep 1
	s_add_i32 s1, s1, 1
	s_cmp_lt_u32 s1, 0x40000
	s_cbranch_scc1 .Lfb1_poll

; __device__ __forceinline__ unsigned xb_ld(unsigned* p)              { return __hip_atomic_load(p, __ATOMIC_RELAXED, __HIP_MEMORY_SCOPE_AGENT); }
; __device__ __forceinline__ unsigned xb_add(unsigned* p, unsigned v) { return __hip_atomic_fetch_add(p, v, __ATOMIC_RELAXED, __HIP_MEMORY_SCOPE_AGENT); }
; #define XB_SPIN(cond, bar) do { unsigned _sp = 0; while (cond) { __builtin_amdgcn_s_sleep(1); \
;     if ((++_sp & 255u) == 0u) { if (xb_ld(&(bar)[XB_TMO])) break; if (_sp > XB_SPIN_CAP) { atomicAdd(&(bar)[XB_TMO], 1u); break; } } } } while (0)
; __device__ __forceinline__ void xcd_barrier(const XcdBarrier& b) {
;     asm volatile("s_waitcnt vmcnt(0)" ::: "memory");
;     __syncthreads();
;     if (threadIdx.x == 0) {
;         unsigned* bar = b.bar;
;         __builtin_amdgcn_s_waitcnt(0);
;         unsigned nloc = b.st[0], nx = b.st[1];
;         if (nloc == 0u) { xcd_barrier_complete(bar, b.x, nloc, nx); b.st[0] = nloc; b.st[1] = nx; }
;         const unsigned old = xb_add(&bar[XB_XSUB(b.x)], 1u);
;         const unsigned gen = old / nloc;
;         if (old + 1u == (gen + 1u) * nloc) {
;             __builtin_amdgcn_fence(__ATOMIC_RELEASE, "agent");
;             asm volatile("s_waitcnt vmcnt(0)" ::: "memory");
;             const unsigned og = xb_add(&bar[XB_TOP], 1u);
;             const unsigned tg = og / nx;
;             if (og + 1u == (tg + 1u) * nx) xb_add(&bar[XB_TOPGEN], 1u);
;             else XB_SPIN(xb_ld(&bar[XB_TOPGEN]) == tg, bar);
;             __builtin_amdgcn_fence(__ATOMIC_ACQUIRE, "agent");
;             xb_add(&bar[XB_XGEN(b.x)], 1u);
;             asm volatile("s_waitcnt vmcnt(0)" ::: "memory");
;         } else {
;             XB_SPIN(xb_ld(&bar[XB_XGEN(b.x)]) == gen, bar);
;             __builtin_amdgcn_fence(__ATOMIC_ACQUIRE, "agent");
;             asm volatile("s_waitcnt vmcnt(0)" ::: "memory");
;         }
;     }
;     __syncthreads();
; }
.LBB0_694:
	s_cmp_gt_i32 s77, 3
	s_cselect_b64 s[6:7], -1, 0
	s_and_b64 s[4:5], s[44:45], s[6:7]
	s_andn2_b64 vcc, exec, s[4:5]
	s_cbranch_vccnz .LBB0_748
	s_waitcnt vmcnt(0) lgkmcnt(0)
	s_barrier
	s_and_saveexec_b64 s[8:9], s[96:97]
	s_cbranch_execz .Lfb2_end
	buffer_inv sc1
	v_mov_b32_e32 v1, 0x20160
	ds_read2_b32 v[2:3], v1 offset1:1
	s_lshl_b32 s1, s0, 8
	s_add_u32 s10, s78, s1
	s_addc_u32 s11, s79, 0
	v_mov_b32_e32 v4, 0x1000
	v_mov_b32_e32 v5, 1
	global_atomic_add v6, v4, v5, s[10:11] offset:1024 sc0
	s_waitcnt vmcnt(0) lgkmcnt(0)
	v_readfirstlane_b32 s3, v6
	v_readfirstlane_b32 s12, v2
	v_readfirstlane_b32 s13, v3
	s_add_i32 s3, s3, 1
	s_mul_i32 s1, s12, 3
	s_cmp_lg_u32 s3, s1
	s_cbranch_scc1 .Lfb2_spin
	buffer_wbl2 sc1
	s_waitcnt vmcnt(0)
.Lfb2_nowb:
	v_mov_b32_e32 v4, 0x3000
	global_atomic_add v6, v4, v5, s[78:79] offset:1024 sc0
	s_waitcnt vmcnt(0)
	v_readfirstlane_b32 s3, v6
	s_add_i32 s3, s3, 1
	s_mul_i32 s13, s13, 3
	s_cmp_lg_u32 s3, s13
	s_cbranch_scc1 .Lfb2_spin
	v_mov_b32_e32 v4, 0x3400
	global_atomic_add v4, v5, s[78:79] offset:256

; __device__ __forceinline__ unsigned xb_ld(unsigned* p)              { return __hip_atomic_load(p, __ATOMIC_RELAXED, __HIP_MEMORY_SCOPE_AGENT); }
; __device__ __forceinline__ unsigned xb_add(unsigned* p, unsigned v) { return __hip_atomic_fetch_add(p, v, __ATOMIC_RELAXED, __HIP_MEMORY_SCOPE_AGENT); }
; #define XB_SPIN(cond, bar) do { unsigned _sp = 0; while (cond) { __builtin_amdgcn_s_sleep(1); \
;     if ((++_sp & 255u) == 0u) { if (xb_ld(&(bar)[XB_TMO])) break; if (_sp > XB_SPIN_CAP) { atomicAdd(&(bar)[XB_TMO], 1u); break; } } } } while (0)
; __device__ __forceinline__ void xcd_barrier(const XcdBarrier& b) {
;     ...
;             const unsigned og = xb_add(&bar[XB_TOP], 1u);
;             const unsigned tg = og / nx;
;             if (og + 1u == (tg + 1u) * nx) xb_add(&bar[XB_TOPGEN], 1u);
;             else XB_SPIN(xb_ld(&bar[XB_TOPGEN]) == tg, bar);
;             __builtin_amdgcn_fence(__ATOMIC_ACQUIRE, "agent");
;             xb_add(&bar[XB_XGEN(b.x)], 1u);
.Lfb2_poll:
	global_load_dword v6, v4, s[78:79] offset:256 sc1
	s_waitcnt vmcnt(0)
	v_readfirstlane_b32 s3, v6
	s_cmp_lg_u32 s3, 2
	s_cbranch_scc1 .Lfb2_end
	s_sleep 1
	s_add_i32 s1, s1, 1
	s_cmp_lt_u32 s1, 0x40000
	s_cbranch_scc1 .Lfb2_poll

; __device__ __forceinline__ unsigned xb_ld(unsigned* p)              { return __hip_atomic_load(p, __ATOMIC_RELAXED, __HIP_MEMORY_SCOPE_AGENT); }
; __device__ __forceinline__ unsigned xb_add(unsigned* p, unsigned v) { return __hip_atomic_fetch_add(p, v, __ATOMIC_RELAXED, __HIP_MEMORY_SCOPE_AGENT); }
; #define XB_SPIN(cond, bar) do { unsigned _sp = 0; while (cond) { __builtin_amdgcn_s_sleep(1); \
;     if ((++_sp & 255u) == 0u) { if (xb_ld(&(bar)[XB_TMO])) break; if (_sp > XB_SPIN_CAP) { atomicAdd(&(bar)[XB_TMO], 1u); break; } } } } while (0)
; __device__ __forceinline__ void xcd_barrier(const XcdBarrier& b) {
;     asm volatile("s_waitcnt vmcnt(0)" ::: "memory");
;     __syncthreads();
;     if (threadIdx.x == 0) {
;         unsigned* bar = b.bar;
;         __builtin_amdgcn_s_waitcnt(0);
;         unsigned nloc = b.st[0], nx = b.st[1];
;         if (nloc == 0u) { xcd_barrier_complete(bar, b.x, nloc, nx); b.st[0] = nloc; b.st[1] = nx; }
;         const unsigned old = xb_add(&bar[XB_XSUB(b.x)], 1u);
;         const unsigned gen = old / nloc;
;         if (old + 1u == (gen + 1u) * nloc) {
;             __builtin_amdgcn_fence(__ATOMIC_RELEASE, "agent");
;             asm volatile("s_waitcnt vmcnt(0)" ::: "memory");
;             const unsigned og = xb_add(&bar[XB_TOP], 1u);
;             const unsigned tg = og / nx;
;             if (og + 1u == (tg + 1u) * nx) xb_add(&bar[XB_TOPGEN], 1u);
;             else XB_SPIN(xb_ld(&bar[XB_TOPGEN]) == tg, bar);
;             __builtin_amdgcn_fence(__ATOMIC_ACQUIRE, "agent");
;             xb_add(&bar[XB_XGEN(b.x)], 1u);
;             asm volatile("s_waitcnt vmcnt(0)" ::: "memory");
;         } else {
;             XB_SPIN(xb_ld(&bar[XB_XGEN(b.x)]) == gen, bar);
;             __builtin_amdgcn_fence(__ATOMIC_ACQUIRE, "agent");
;             asm volatile("s_waitcnt vmcnt(0)" ::: "memory");
;         }
;     }
;     __syncthreads();
; }
.LBB0_978:
	s_cmp_gt_i32 s77, 4
	s_cselect_b64 s[6:7], -1, 0
	s_and_b64 s[4:5], s[14:15], s[6:7]
	s_andn2_b64 vcc, exec, s[4:5]
	s_cbranch_vccnz .LBB0_1032
	s_waitcnt vmcnt(0) lgkmcnt(0)
	s_barrier
	s_and_saveexec_b64 s[8:9], s[96:97]
	s_cbranch_execz .Lfb3_end
	buffer_inv sc1
	v_mov_b32_e32 v1, 0x20160
	ds_read2_b32 v[2:3], v1 offset1:1
	s_lshl_b32 s1, s0, 8
	s_add_u32 s10, s78, s1
	s_addc_u32 s11, s79, 0
	v_mov_b32_e32 v4, 0x1000
	v_mov_b32_e32 v5, 1
	global_atomic_add v6, v4, v5, s[10:11] offset:1024 sc0
	s_waitcnt vmcnt(0) lgkmcnt(0)
	v_readfirstlane_b32 s3, v6
	v_readfirstlane_b32 s12, v2
	v_readfirstlane_b32 s13, v3
	s_add_i32 s3, s3, 1
	s_mul_i32 s1, s12, 4
	s_cmp_lg_u32 s3, s1
	s_cbranch_scc1 .Lfb3_spin
	buffer_wbl2 sc1
	s_waitcnt vmcnt(0)
.Lfb3_nowb:
	v_mov_b32_e32 v4, 0x3000
	global_atomic_add v6, v4, v5, s[78:79] offset:1024 sc0
	s_waitcnt vmcnt(0)
	v_readfirstlane_b32 s3, v6
	s_add_i32 s3, s3, 1
	s_mul_i32 s13, s13, 4
	s_cmp_lg_u32 s3, s13
	s_cbranch_scc1 .Lfb3_spin
	v_mov_b32_e32 v4, 0x3400
	global_atomic_add v4, v5, s[78:79] offset:256

; __device__ __forceinline__ unsigned xb_ld(unsigned* p)              { return __hip_atomic_load(p, __ATOMIC_RELAXED, __HIP_MEMORY_SCOPE_AGENT); }
; __device__ __forceinline__ unsigned xb_add(unsigned* p, unsigned v) { return __hip_atomic_fetch_add(p, v, __ATOMIC_RELAXED, __HIP_MEMORY_SCOPE_AGENT); }
; #define XB_SPIN(cond, bar) do { unsigned _sp = 0; while (cond) { __builtin_amdgcn_s_sleep(1); \
;     if ((++_sp & 255u) == 0u) { if (xb_ld(&(bar)[XB_TMO])) break; if (_sp > XB_SPIN_CAP) { atomicAdd(&(bar)[XB_TMO], 1u); break; } } } } while (0)
; __device__ __forceinline__ void xcd_barrier(const XcdBarrier& b) {
;     ...
;             const unsigned og = xb_add(&bar[XB_TOP], 1u);
;             const unsigned tg = og / nx;
;             if (og + 1u == (tg + 1u) * nx) xb_add(&bar[XB_TOPGEN], 1u);
;             else XB_SPIN(xb_ld(&bar[XB_TOPGEN]) == tg, bar);
;             __builtin_amdgcn_fence(__ATOMIC_ACQUIRE, "agent");
;             xb_add(&bar[XB_XGEN(b.x)], 1u);
.Lfb3_poll:
	global_load_dword v6, v4, s[78:79] offset:256 sc1
	s_waitcnt vmcnt(0)
	v_readfirstlane_b32 s3, v6
	s_cmp_lg_u32 s3, 3
	s_cbranch_scc1 .Lfb3_end
	s_sleep 1
	s_add_i32 s1, s1, 1
	s_cmp_lt_u32 s1, 0x40000
	s_cbranch_scc1 .Lfb3_poll

; __device__ __forceinline__ unsigned xb_ld(unsigned* p)              { return __hip_atomic_load(p, __ATOMIC_RELAXED, __HIP_MEMORY_SCOPE_AGENT); }
; __device__ __forceinline__ unsigned xb_add(unsigned* p, unsigned v) { return __hip_atomic_fetch_add(p, v, __ATOMIC_RELAXED, __HIP_MEMORY_SCOPE_AGENT); }
; #define XB_SPIN(cond, bar) do { unsigned _sp = 0; while (cond) { __builtin_amdgcn_s_sleep(1); \
;     if ((++_sp & 255u) == 0u) { if (xb_ld(&(bar)[XB_TMO])) break; if (_sp > XB_SPIN_CAP) { atomicAdd(&(bar)[XB_TMO], 1u); break; } } } } while (0)
; __device__ __forceinline__ void xcd_barrier(const XcdBarrier& b) {
;     asm volatile("s_waitcnt vmcnt(0)" ::: "memory");
;     __syncthreads();
;     if (threadIdx.x == 0) {
;         unsigned* bar = b.bar;
;         __builtin_amdgcn_s_waitcnt(0);
;         unsigned nloc = b.st[0], nx = b.st[1];
;         if (nloc == 0u) { xcd_barrier_complete(bar, b.x, nloc, nx); b.st[0] = nloc; b.st[1] = nx; }
;         const unsigned old = xb_add(&bar[XB_XSUB(b.x)], 1u);
;         const unsigned gen = old / nloc;
;         if (old + 1u == (gen + 1u) * nloc) {
;             __builtin_amdgcn_fence(__ATOMIC_RELEASE, "agent");
;             asm volatile("s_waitcnt vmcnt(0)" ::: "memory");
;             const unsigned og = xb_add(&bar[XB_TOP], 1u);
;             const unsigned tg = og / nx;
;             if (og + 1u == (tg + 1u) * nx) xb_add(&bar[XB_TOPGEN], 1u);
;             else XB_SPIN(xb_ld(&bar[XB_TOPGEN]) == tg, bar);
;             __builtin_amdgcn_fence(__ATOMIC_ACQUIRE, "agent");
;             xb_add(&bar[XB_XGEN(b.x)], 1u);
;             asm volatile("s_waitcnt vmcnt(0)" ::: "memory");
;         } else {
;             XB_SPIN(xb_ld(&bar[XB_XGEN(b.x)]) == gen, bar);
;             __builtin_amdgcn_fence(__ATOMIC_ACQUIRE, "agent");
;             asm volatile("s_waitcnt vmcnt(0)" ::: "memory");
;         }
;     }
;     __syncthreads();
; }
.LBB0_1058:
	s_cmp_gt_i32 s77, 5
	s_cselect_b64 s[6:7], -1, 0
	s_and_b64 s[4:5], s[22:23], s[6:7]
	s_andn2_b64 vcc, exec, s[4:5]
	s_cbranch_vccnz .LBB0_1112
	s_waitcnt vmcnt(0) lgkmcnt(0)
	s_barrier
	s_and_saveexec_b64 s[8:9], s[96:97]
	s_cbranch_execz .Lfb4_end
	buffer_inv sc1
	v_mov_b32_e32 v1, 0x20160
	ds_read2_b32 v[2:3], v1 offset1:1
	s_lshl_b32 s1, s0, 8
	s_add_u32 s10, s78, s1
	s_addc_u32 s11, s79, 0
	v_mov_b32_e32 v4, 0x1000
	v_mov_b32_e32 v5, 1
	global_atomic_add v6, v4, v5, s[10:11] offset:1024 sc0
	s_waitcnt vmcnt(0) lgkmcnt(0)
	v_readfirstlane_b32 s3, v6
	v_readfirstlane_b32 s12, v2
	v_readfirstlane_b32 s13, v3
	s_add_i32 s3, s3, 1
	s_mul_i32 s1, s12, 5
	s_cmp_lg_u32 s3, s1
	s_cbranch_scc1 .Lfb4_spin
	buffer_wbl2 sc1
	s_waitcnt vmcnt(0)
.Lfb4_nowb:
	v_mov_b32_e32 v4, 0x3000
	global_atomic_add v6, v4, v5, s[78:79] offset:1024 sc0
	s_waitcnt vmcnt(0)
	v_readfirstlane_b32 s3, v6
	s_add_i32 s3, s3, 1
	s_mul_i32 s13, s13, 5
	s_cmp_lg_u32 s3, s13
	s_cbranch_scc1 .Lfb4_spin
	v_mov_b32_e32 v4, 0x3400
	global_atomic_add v4, v5, s[78:79] offset:256

; __device__ __forceinline__ unsigned xb_ld(unsigned* p)              { return __hip_atomic_load(p, __ATOMIC_RELAXED, __HIP_MEMORY_SCOPE_AGENT); }
; __device__ __forceinline__ unsigned xb_add(unsigned* p, unsigned v) { return __hip_atomic_fetch_add(p, v, __ATOMIC_RELAXED, __HIP_MEMORY_SCOPE_AGENT); }
; #define XB_SPIN(cond, bar) do { unsigned _sp = 0; while (cond) { __builtin_amdgcn_s_sleep(1); \
;     if ((++_sp & 255u) == 0u) { if (xb_ld(&(bar)[XB_TMO])) break; if (_sp > XB_SPIN_CAP) { atomicAdd(&(bar)[XB_TMO], 1u); break; } } } } while (0)
; __device__ __forceinline__ void xcd_barrier(const XcdBarrier& b) {
;     ...
;             const unsigned og = xb_add(&bar[XB_TOP], 1u);
;             const unsigned tg = og / nx;
;             if (og + 1u == (tg + 1u) * nx) xb_add(&bar[XB_TOPGEN], 1u);
;             else XB_SPIN(xb_ld(&bar[XB_TOPGEN]) == tg, bar);
;             __builtin_amdgcn_fence(__ATOMIC_ACQUIRE, "agent");
;             xb_add(&bar[XB_XGEN(b.x)], 1u);
.Lfb4_poll:
	global_load_dword v6, v4, s[78:79] offset:256 sc1
	s_waitcnt vmcnt(0)
	v_readfirstlane_b32 s3, v6
	s_cmp_lg_u32 s3, 4
	s_cbranch_scc1 .Lfb4_end
	s_sleep 1
	s_add_i32 s1, s1, 1
	s_cmp_lt_u32 s1, 0x40000
	s_cbranch_scc1 .Lfb4_poll

; __device__ __forceinline__ unsigned xb_ld(unsigned* p)              { return __hip_atomic_load(p, __ATOMIC_RELAXED, __HIP_MEMORY_SCOPE_AGENT); }
; __device__ __forceinline__ unsigned xb_add(unsigned* p, unsigned v) { return __hip_atomic_fetch_add(p, v, __ATOMIC_RELAXED, __HIP_MEMORY_SCOPE_AGENT); }
; #define XB_SPIN(cond, bar) do { unsigned _sp = 0; while (cond) { __builtin_amdgcn_s_sleep(1); \
;     if ((++_sp & 255u) == 0u) { if (xb_ld(&(bar)[XB_TMO])) break; if (_sp > XB_SPIN_CAP) { atomicAdd(&(bar)[XB_TMO], 1u); break; } } } } while (0)
; __device__ __forceinline__ void xcd_barrier(const XcdBarrier& b) {
;     asm volatile("s_waitcnt vmcnt(0)" ::: "memory");
;     __syncthreads();
;     if (threadIdx.x == 0) {
;         unsigned* bar = b.bar;
;         __builtin_amdgcn_s_waitcnt(0);
;         unsigned nloc = b.st[0], nx = b.st[1];
;         if (nloc == 0u) { xcd_barrier_complete(bar, b.x, nloc, nx); b.st[0] = nloc; b.st[1] = nx; }
;         const unsigned old = xb_add(&bar[XB_XSUB(b.x)], 1u);
;         const unsigned gen = old / nloc;
;         if (old + 1u == (gen + 1u) * nloc) {
;             __builtin_amdgcn_fence(__ATOMIC_RELEASE, "agent");
;             asm volatile("s_waitcnt vmcnt(0)" ::: "memory");
;             const unsigned og = xb_add(&bar[XB_TOP], 1u);
;             const unsigned tg = og / nx;
;             if (og + 1u == (tg + 1u) * nx) xb_add(&bar[XB_TOPGEN], 1u);
;             else XB_SPIN(xb_ld(&bar[XB_TOPGEN]) == tg, bar);
;             __builtin_amdgcn_fence(__ATOMIC_ACQUIRE, "agent");
;             xb_add(&bar[XB_XGEN(b.x)], 1u);
;             asm volatile("s_waitcnt vmcnt(0)" ::: "memory");
;         } else {
;             XB_SPIN(xb_ld(&bar[XB_XGEN(b.x)]) == gen, bar);
;             __builtin_amdgcn_fence(__ATOMIC_ACQUIRE, "agent");
;             asm volatile("s_waitcnt vmcnt(0)" ::: "memory");
;         }
;     }
;     __syncthreads();
; }
.LBB0_1157:
	s_cmp_gt_i32 s77, 6
	s_waitcnt lgkmcnt(0)
	s_cselect_b64 s[6:7], -1, 0
	s_and_b64 s[4:5], s[20:21], s[6:7]
	s_andn2_b64 vcc, exec, s[4:5]
	s_cbranch_vccnz .LBB0_1211
	s_waitcnt vmcnt(0) lgkmcnt(0)
	s_barrier
	s_and_saveexec_b64 s[8:9], s[96:97]
	s_cbranch_execz .Lfb5_end
	buffer_inv sc1
	v_mov_b32_e32 v1, 0x20160
	ds_read2_b32 v[2:3], v1 offset1:1
	s_lshl_b32 s1, s0, 8
	s_add_u32 s10, s78, s1
	s_addc_u32 s11, s79, 0
	v_mov_b32_e32 v4, 0x1000
	v_mov_b32_e32 v5, 1
	global_atomic_add v6, v4, v5, s[10:11] offset:1024 sc0
	s_waitcnt vmcnt(0) lgkmcnt(0)
	v_readfirstlane_b32 s3, v6
	v_readfirstlane_b32 s12, v2
	v_readfirstlane_b32 s13, v3
	s_add_i32 s3, s3, 1
	s_mul_i32 s1, s12, 6
	s_cmp_lg_u32 s3, s1
	s_cbranch_scc1 .Lfb5_spin
	buffer_wbl2 sc1
	s_waitcnt vmcnt(0)
.Lfb5_nowb:
	v_mov_b32_e32 v4, 0x3000
	global_atomic_add v6, v4, v5, s[78:79] offset:1024 sc0
	s_waitcnt vmcnt(0)
	v_readfirstlane_b32 s3, v6
	s_add_i32 s3, s3, 1
	s_mul_i32 s13, s13, 6
	s_cmp_lg_u32 s3, s13
	s_cbranch_scc1 .Lfb5_spin
	v_mov_b32_e32 v4, 0x3400
	global_atomic_add v4, v5, s[78:79] offset:256

; __device__ __forceinline__ unsigned xb_ld(unsigned* p)              { return __hip_atomic_load(p, __ATOMIC_RELAXED, __HIP_MEMORY_SCOPE_AGENT); }
; __device__ __forceinline__ unsigned xb_add(unsigned* p, unsigned v) { return __hip_atomic_fetch_add(p, v, __ATOMIC_RELAXED, __HIP_MEMORY_SCOPE_AGENT); }
; #define XB_SPIN(cond, bar) do { unsigned _sp = 0; while (cond) { __builtin_amdgcn_s_sleep(1); \
;     if ((++_sp & 255u) == 0u) { if (xb_ld(&(bar)[XB_TMO])) break; if (_sp > XB_SPIN_CAP) { atomicAdd(&(bar)[XB_TMO], 1u); break; } } } } while (0)
; __device__ __forceinline__ void xcd_barrier(const XcdBarrier& b) {
;     ...
;             const unsigned og = xb_add(&bar[XB_TOP], 1u);
;             const unsigned tg = og / nx;
;             if (og + 1u == (tg + 1u) * nx) xb_add(&bar[XB_TOPGEN], 1u);
;             else XB_SPIN(xb_ld(&bar[XB_TOPGEN]) == tg, bar);
;             __builtin_amdgcn_fence(__ATOMIC_ACQUIRE, "agent");
;             xb_add(&bar[XB_XGEN(b.x)], 1u);
.Lfb5_poll:
	global_load_dword v6, v4, s[78:79] offset:256 sc1
	s_waitcnt vmcnt(0)
	v_readfirstlane_b32 s3, v6
	s_cmp_lg_u32 s3, 5
	s_cbranch_scc1 .Lfb5_end
	s_sleep 1
	s_add_i32 s1, s1, 1
	s_cmp_lt_u32 s1, 0x40000
	s_cbranch_scc1 .Lfb5_poll

; __device__ __forceinline__ unsigned xb_ld(unsigned* p)              { return __hip_atomic_load(p, __ATOMIC_RELAXED, __HIP_MEMORY_SCOPE_AGENT); }
; __device__ __forceinline__ unsigned xb_add(unsigned* p, unsigned v) { return __hip_atomic_fetch_add(p, v, __ATOMIC_RELAXED, __HIP_MEMORY_SCOPE_AGENT); }
; #define XB_SPIN(cond, bar) do { unsigned _sp = 0; while (cond) { __builtin_amdgcn_s_sleep(1); \
;     if ((++_sp & 255u) == 0u) { if (xb_ld(&(bar)[XB_TMO])) break; if (_sp > XB_SPIN_CAP) { atomicAdd(&(bar)[XB_TMO], 1u); break; } } } } while (0)
; __device__ __forceinline__ void xcd_barrier(const XcdBarrier& b) {
;     asm volatile("s_waitcnt vmcnt(0)" ::: "memory");
;     __syncthreads();
;     if (threadIdx.x == 0) {
;         unsigned* bar = b.bar;
;         __builtin_amdgcn_s_waitcnt(0);
;         unsigned nloc = b.st[0], nx = b.st[1];
;         if (nloc == 0u) { xcd_barrier_complete(bar, b.x, nloc, nx); b.st[0] = nloc; b.st[1] = nx; }
;         const unsigned old = xb_add(&bar[XB_XSUB(b.x)], 1u);
;         const unsigned gen = old / nloc;
;         if (old + 1u == (gen + 1u) * nloc) {
;             __builtin_amdgcn_fence(__ATOMIC_RELEASE, "agent");
;             asm volatile("s_waitcnt vmcnt(0)" ::: "memory");
;             const unsigned og = xb_add(&bar[XB_TOP], 1u);
;             const unsigned tg = og / nx;
;             if (og + 1u == (tg + 1u) * nx) xb_add(&bar[XB_TOPGEN], 1u);
;             else XB_SPIN(xb_ld(&bar[XB_TOPGEN]) == tg, bar);
;             __builtin_amdgcn_fence(__ATOMIC_ACQUIRE, "agent");
;             xb_add(&bar[XB_XGEN(b.x)], 1u);
;             asm volatile("s_waitcnt vmcnt(0)" ::: "memory");
;         } else {
;             XB_SPIN(xb_ld(&bar[XB_XGEN(b.x)]) == gen, bar);
;             __builtin_amdgcn_fence(__ATOMIC_ACQUIRE, "agent");
;             asm volatile("s_waitcnt vmcnt(0)" ::: "memory");
;         }
;     }
;     __syncthreads();
; }
.LBB0_1300:
	s_cmp_gt_i32 s77, 7
	s_cselect_b64 s[6:7], -1, 0
	s_and_b64 s[4:5], s[30:31], s[6:7]
	s_andn2_b64 vcc, exec, s[4:5]
	s_cbranch_vccnz .LBB0_1354
	s_waitcnt vmcnt(0) lgkmcnt(0)
	s_barrier
	s_and_saveexec_b64 s[8:9], s[96:97]
	s_cbranch_execz .Lfb6_end
	buffer_inv sc1
	v_mov_b32_e32 v1, 0x20160
	ds_read2_b32 v[2:3], v1 offset1:1
	s_lshl_b32 s1, s0, 8
	s_add_u32 s10, s78, s1
	s_addc_u32 s11, s79, 0
	v_mov_b32_e32 v4, 0x1000
	v_mov_b32_e32 v5, 1
	global_atomic_add v6, v4, v5, s[10:11] offset:1024 sc0
	s_waitcnt vmcnt(0) lgkmcnt(0)
	v_readfirstlane_b32 s3, v6
	v_readfirstlane_b32 s12, v2
	v_readfirstlane_b32 s13, v3
	s_add_i32 s3, s3, 1
	s_mul_i32 s1, s12, 7
	s_cmp_lg_u32 s3, s1
	s_cbranch_scc1 .Lfb6_spin
	buffer_wbl2 sc1
	s_waitcnt vmcnt(0)
.Lfb6_nowb:
	v_mov_b32_e32 v4, 0x3000
	global_atomic_add v6, v4, v5, s[78:79] offset:1024 sc0
	s_waitcnt vmcnt(0)
	v_readfirstlane_b32 s3, v6
	s_add_i32 s3, s3, 1
	s_mul_i32 s13, s13, 7
	s_cmp_lg_u32 s3, s13
	s_cbranch_scc1 .Lfb6_spin
	v_mov_b32_e32 v4, 0x3400
	global_atomic_add v4, v5, s[78:79] offset:256

; __device__ __forceinline__ unsigned xb_ld(unsigned* p)              { return __hip_atomic_load(p, __ATOMIC_RELAXED, __HIP_MEMORY_SCOPE_AGENT); }
; __device__ __forceinline__ unsigned xb_add(unsigned* p, unsigned v) { return __hip_atomic_fetch_add(p, v, __ATOMIC_RELAXED, __HIP_MEMORY_SCOPE_AGENT); }
; #define XB_SPIN(cond, bar) do { unsigned _sp = 0; while (cond) { __builtin_amdgcn_s_sleep(1); \
;     if ((++_sp & 255u) == 0u) { if (xb_ld(&(bar)[XB_TMO])) break; if (_sp > XB_SPIN_CAP) { atomicAdd(&(bar)[XB_TMO], 1u); break; } } } } while (0)
; __device__ __forceinline__ void xcd_barrier(const XcdBarrier& b) {
;     ...
;             const unsigned og = xb_add(&bar[XB_TOP], 1u);
;             const unsigned tg = og / nx;
;             if (og + 1u == (tg + 1u) * nx) xb_add(&bar[XB_TOPGEN], 1u);
;             else XB_SPIN(xb_ld(&bar[XB_TOPGEN]) == tg, bar);
;             __builtin_amdgcn_fence(__ATOMIC_ACQUIRE, "agent");
;             xb_add(&bar[XB_XGEN(b.x)], 1u);
.Lfb6_poll:
	global_load_dword v6, v4, s[78:79] offset:256 sc1
	s_waitcnt vmcnt(0)
	v_readfirstlane_b32 s3, v6
	s_cmp_lg_u32 s3, 6
	s_cbranch_scc1 .Lfb6_end
	s_sleep 1
	s_add_i32 s1, s1, 1
	s_cmp_lt_u32 s1, 0x40000
	s_cbranch_scc1 .Lfb6_poll

; __device__ __forceinline__ unsigned xb_ld(unsigned* p)              { return __hip_atomic_load(p, __ATOMIC_RELAXED, __HIP_MEMORY_SCOPE_AGENT); }
; __device__ __forceinline__ unsigned xb_add(unsigned* p, unsigned v) { return __hip_atomic_fetch_add(p, v, __ATOMIC_RELAXED, __HIP_MEMORY_SCOPE_AGENT); }
; #define XB_SPIN(cond, bar) do { unsigned _sp = 0; while (cond) { __builtin_amdgcn_s_sleep(1); \
;     if ((++_sp & 255u) == 0u) { if (xb_ld(&(bar)[XB_TMO])) break; if (_sp > XB_SPIN_CAP) { atomicAdd(&(bar)[XB_TMO], 1u); break; } } } } while (0)
; __device__ __forceinline__ void xcd_barrier(const XcdBarrier& b) {
;     asm volatile("s_waitcnt vmcnt(0)" ::: "memory");
;     __syncthreads();
;     if (threadIdx.x == 0) {
;         unsigned* bar = b.bar;
;         __builtin_amdgcn_s_waitcnt(0);
;         unsigned nloc = b.st[0], nx = b.st[1];
;         if (nloc == 0u) { xcd_barrier_complete(bar, b.x, nloc, nx); b.st[0] = nloc; b.st[1] = nx; }
;         const unsigned old = xb_add(&bar[XB_XSUB(b.x)], 1u);
;         const unsigned gen = old / nloc;
;         if (old + 1u == (gen + 1u) * nloc) {
;             __builtin_amdgcn_fence(__ATOMIC_RELEASE, "agent");
;             asm volatile("s_waitcnt vmcnt(0)" ::: "memory");
;             const unsigned og = xb_add(&bar[XB_TOP], 1u);
;             const unsigned tg = og / nx;
;             if (og + 1u == (tg + 1u) * nx) xb_add(&bar[XB_TOPGEN], 1u);
;             else XB_SPIN(xb_ld(&bar[XB_TOPGEN]) == tg, bar);
;             __builtin_amdgcn_fence(__ATOMIC_ACQUIRE, "agent");
;             xb_add(&bar[XB_XGEN(b.x)], 1u);
;             asm volatile("s_waitcnt vmcnt(0)" ::: "memory");
;         } else {
;             XB_SPIN(xb_ld(&bar[XB_XGEN(b.x)]) == gen, bar);
;             __builtin_amdgcn_fence(__ATOMIC_ACQUIRE, "agent");
;             asm volatile("s_waitcnt vmcnt(0)" ::: "memory");
;         }
;     }
;     __syncthreads();
; }
.LBB0_1383:
	s_cmp_gt_i32 s77, 8
	s_cselect_b64 s[6:7], -1, 0
	s_and_b64 s[4:5], s[10:11], s[6:7]
	s_andn2_b64 vcc, exec, s[4:5]
	s_cbranch_vccnz .LBB0_1437
	s_waitcnt vmcnt(0) lgkmcnt(0)
	s_barrier
	s_and_saveexec_b64 s[8:9], s[96:97]
	s_cbranch_execz .Lfb7_end
	buffer_inv sc1
	v_mov_b32_e32 v1, 0x20160
	ds_read2_b32 v[2:3], v1 offset1:1
	s_lshl_b32 s1, s0, 8
	s_add_u32 s10, s78, s1
	s_addc_u32 s11, s79, 0
	v_mov_b32_e32 v4, 0x1000
	v_mov_b32_e32 v5, 1
	global_atomic_add v6, v4, v5, s[10:11] offset:1024 sc0
	s_waitcnt vmcnt(0) lgkmcnt(0)
	v_readfirstlane_b32 s3, v6
	v_readfirstlane_b32 s12, v2
	v_readfirstlane_b32 s13, v3
	s_add_i32 s3, s3, 1
	s_mul_i32 s1, s12, 8
	s_cmp_lg_u32 s3, s1
	s_cbranch_scc1 .Lfb7_spin
	s_lshl_b32 s28, s0, 2
	v_mov_b32_e32 v22, s28
	global_load_dword v22, v22, s[78:79] offset:64 sc1
	s_and_b32 s29, s2, 7
	s_lshl_b32 s29, 1, s29
	s_waitcnt vmcnt(0)
	v_readfirstlane_b32 s31, v22
	s_lshl_b32 s30, s12, 3
	s_cmpk_lg_i32 s74, 0x100
	s_cbranch_scc1 .Lfb7_wb
	s_cmp_lg_u32 s30, s74
	s_cbranch_scc1 .Lfb7_wb
	s_cmp_eq_u32 s31, s29
	s_cbranch_scc1 .Lfb7_nowb
.Lfb7_wb:
	buffer_wbl2 sc1
	s_waitcnt vmcnt(0)
.Lfb7_nowb:
	v_mov_b32_e32 v4, 0x3000
	global_atomic_add v6, v4, v5, s[78:79] offset:1024 sc0
	s_waitcnt vmcnt(0)
	v_readfirstlane_b32 s3, v6
	s_add_i32 s3, s3, 1
	s_mul_i32 s13, s13, 8
	s_cmp_lg_u32 s3, s13
	s_cbranch_scc1 .Lfb7_spin
	v_mov_b32_e32 v4, 0x3400
	global_atomic_add v4, v5, s[78:79] offset:256

; __device__ __forceinline__ unsigned xb_ld(unsigned* p)              { return __hip_atomic_load(p, __ATOMIC_RELAXED, __HIP_MEMORY_SCOPE_AGENT); }
; __device__ __forceinline__ unsigned xb_add(unsigned* p, unsigned v) { return __hip_atomic_fetch_add(p, v, __ATOMIC_RELAXED, __HIP_MEMORY_SCOPE_AGENT); }
; #define XB_SPIN(cond, bar) do { unsigned _sp = 0; while (cond) { __builtin_amdgcn_s_sleep(1); \
;     if ((++_sp & 255u) == 0u) { if (xb_ld(&(bar)[XB_TMO])) break; if (_sp > XB_SPIN_CAP) { atomicAdd(&(bar)[XB_TMO], 1u); break; } } } } while (0)
; __device__ __forceinline__ void xcd_barrier(const XcdBarrier& b) {
;     ...
;             const unsigned og = xb_add(&bar[XB_TOP], 1u);
;             const unsigned tg = og / nx;
;             if (og + 1u == (tg + 1u) * nx) xb_add(&bar[XB_TOPGEN], 1u);
;             else XB_SPIN(xb_ld(&bar[XB_TOPGEN]) == tg, bar);
;             __builtin_amdgcn_fence(__ATOMIC_ACQUIRE, "agent");
;             xb_add(&bar[XB_XGEN(b.x)], 1u);
.Lfb7_poll:
	global_load_dword v6, v4, s[78:79] offset:256 sc1
	s_waitcnt vmcnt(0)
	v_readfirstlane_b32 s3, v6
	s_cmp_lg_u32 s3, 7
	s_cbranch_scc1 .Lfb7_end
	s_sleep 1
	s_add_i32 s1, s1, 1
	s_cmp_lt_u32 s1, 0x40000
	s_cbranch_scc1 .Lfb7_poll
